# GEMM K-loop: all SGPR-based LDS-DMA loads in scalar-base form (no per-load 64-bit VALU address add), late half-step base in s[98:99], literal M0 stage offsets
# speedup vs baseline: 1.0033x; 1.0033x over previous
.LBB0_760:
	s_add_i32 s38, s46, 2
	s_add_u32 s8, s26, s4
	s_addc_u32 s9, s27, s5
	s_add_u32 s8, s8, 0x100
	s_addc_u32 s9, s9, 0
	s_add_u32 s30, s44, s4
	s_addc_u32 s31, s45, s5
	v_add_u32_e32 v252, 0x10000, v193
	ds_read_b128 v[132:135], v252
	ds_read_b128 v[136:139], v252 offset:1024
	ds_read_b128 v[140:143], v252 offset:2048
	ds_read_b128 v[144:147], v252 offset:3072
	s_cmp_eq_u32 s71, s46
	s_cselect_b32 s9, s13, s9
	s_cselect_b32 s8, s12, s8
	s_cselect_b32 s31, s57, s31
	s_cselect_b32 s30, s56, s30
	v_lshl_add_u64 v[190:191], v[128:129], 0, s[4:5]
	s_add_i32 m0, s19, 0xc000
	ds_read_b128 v[148:151], v202
	ds_read_b128 v[152:155], v202 offset:1024
	ds_read_b128 v[156:159], v202 offset:2048
	ds_read_b128 v[160:163], v202 offset:3072
	ds_read_b128 v[164:167], v202 offset:4096
	ds_read_b128 v[204:207], v202 offset:5120
	ds_read_b128 v[208:211], v202 offset:6144
	ds_read_b128 v[212:215], v202 offset:7168
	global_load_lds_dwordx4 v[190:191], off
	s_add_i32 m0, s19, 0xe000
	v_lshl_add_u64 v[190:191], v[130:131], 0, s[4:5]
	global_load_lds_dwordx4 v[190:191], off
	s_waitcnt lgkmcnt(8)
	s_barrier
	s_waitcnt lgkmcnt(0)
	v_mfma_f32_16x16x32_bf16 v[124:127], v[132:135], v[148:151], v[124:127]
	v_mfma_f32_16x16x32_bf16 v[120:123], v[140:143], v[148:151], v[120:123]
	v_mfma_f32_16x16x32_bf16 v[108:111], v[132:135], v[156:159], v[108:111]
	v_mfma_f32_16x16x32_bf16 v[104:107], v[140:143], v[156:159], v[104:107]
	v_mfma_f32_16x16x32_bf16 v[92:95], v[132:135], v[164:167], v[92:95]
	v_mfma_f32_16x16x32_bf16 v[88:91], v[140:143], v[164:167], v[88:91]
	v_mfma_f32_16x16x32_bf16 v[76:79], v[132:135], v[208:211], v[76:79]
	v_mfma_f32_16x16x32_bf16 v[72:75], v[140:143], v[208:211], v[72:75]
	v_mfma_f32_16x16x32_bf16 v[124:127], v[136:139], v[152:155], v[124:127]
	v_mfma_f32_16x16x32_bf16 v[120:123], v[144:147], v[152:155], v[120:123]
	v_mfma_f32_16x16x32_bf16 v[108:111], v[136:139], v[160:163], v[108:111]
	v_mfma_f32_16x16x32_bf16 v[104:107], v[144:147], v[160:163], v[104:107]
	v_mfma_f32_16x16x32_bf16 v[92:95], v[136:139], v[204:207], v[92:95]
	v_mfma_f32_16x16x32_bf16 v[88:91], v[144:147], v[204:207], v[88:91]
	v_mfma_f32_16x16x32_bf16 v[76:79], v[136:139], v[212:215], v[76:79]
	v_mfma_f32_16x16x32_bf16 v[72:75], v[144:147], v[212:215], v[72:75]
	s_barrier
	ds_read_b128 v[216:219], v252 offset:16384
	ds_read_b128 v[220:223], v252 offset:17408
	ds_read_b128 v[232:235], v252 offset:18432
	ds_read_b128 v[240:243], v252 offset:19456
	s_add_i32 m0, s53, 0x10000
	s_nop 0
	global_load_lds_dwordx4 v180, s[30:31]
	s_add_i32 m0, s53, 0x12000
	s_nop 0
	global_load_lds_dwordx4 v176, s[30:31]
	s_barrier
	s_waitcnt lgkmcnt(0)
	v_mfma_f32_16x16x32_bf16 v[116:119], v[216:219], v[148:151], v[116:119]
	v_mfma_f32_16x16x32_bf16 v[112:115], v[232:235], v[148:151], v[112:115]
	v_mfma_f32_16x16x32_bf16 v[100:103], v[216:219], v[156:159], v[100:103]
	v_mfma_f32_16x16x32_bf16 v[96:99], v[232:235], v[156:159], v[96:99]
	v_mfma_f32_16x16x32_bf16 v[84:87], v[216:219], v[164:167], v[84:87]
	v_mfma_f32_16x16x32_bf16 v[80:83], v[232:235], v[164:167], v[80:83]
	v_mfma_f32_16x16x32_bf16 v[68:71], v[216:219], v[208:211], v[68:71]
	v_mfma_f32_16x16x32_bf16 v[64:67], v[232:235], v[208:211], v[64:67]
	v_mfma_f32_16x16x32_bf16 v[116:119], v[220:223], v[152:155], v[116:119]
	v_mfma_f32_16x16x32_bf16 v[112:115], v[240:243], v[152:155], v[112:115]
	v_mfma_f32_16x16x32_bf16 v[100:103], v[220:223], v[160:163], v[100:103]
	v_mfma_f32_16x16x32_bf16 v[96:99], v[240:243], v[160:163], v[96:99]
	v_mfma_f32_16x16x32_bf16 v[84:87], v[220:223], v[204:207], v[84:87]
	v_mfma_f32_16x16x32_bf16 v[80:83], v[240:243], v[204:207], v[80:83]
	v_mfma_f32_16x16x32_bf16 v[68:71], v[220:223], v[212:215], v[68:71]
	v_mfma_f32_16x16x32_bf16 v[64:67], v[240:243], v[212:215], v[64:67]
	s_mov_b32 m0, s19
	s_barrier
	ds_read_b128 v[148:151], v202 offset:16384
	ds_read_b128 v[152:155], v202 offset:17408
	ds_read_b128 v[156:159], v202 offset:18432
	ds_read_b128 v[160:163], v202 offset:19456
	ds_read_b128 v[164:167], v202 offset:20480
	ds_read_b128 v[204:207], v202 offset:21504
	ds_read_b128 v[208:211], v202 offset:22528
	ds_read_b128 v[212:215], v202 offset:23552
	global_load_lds_dwordx4 v178, s[8:9]
	s_mov_b32 m0, s21
	s_nop 0
	global_load_lds_dwordx4 v174, s[8:9]
	s_barrier
	s_waitcnt lgkmcnt(0)
	v_mfma_f32_16x16x32_bf16 v[60:63], v[132:135], v[148:151], v[60:63]
	v_mfma_f32_16x16x32_bf16 v[56:59], v[140:143], v[148:151], v[56:59]
	v_mfma_f32_16x16x32_bf16 v[44:47], v[132:135], v[156:159], v[44:47]
	v_mfma_f32_16x16x32_bf16 v[40:43], v[140:143], v[156:159], v[40:43]
	v_mfma_f32_16x16x32_bf16 v[28:31], v[132:135], v[164:167], v[28:31]
	v_mfma_f32_16x16x32_bf16 v[24:27], v[140:143], v[164:167], v[24:27]
	v_mfma_f32_16x16x32_bf16 v[12:15], v[132:135], v[208:211], v[12:15]
	v_mfma_f32_16x16x32_bf16 v[8:11], v[140:143], v[208:211], v[8:11]
	v_mfma_f32_16x16x32_bf16 v[60:63], v[136:139], v[152:155], v[60:63]
	v_mfma_f32_16x16x32_bf16 v[56:59], v[144:147], v[152:155], v[56:59]
	v_mfma_f32_16x16x32_bf16 v[44:47], v[136:139], v[160:163], v[44:47]
	v_mfma_f32_16x16x32_bf16 v[40:43], v[144:147], v[160:163], v[40:43]
	v_mfma_f32_16x16x32_bf16 v[28:31], v[136:139], v[204:207], v[28:31]
	v_mfma_f32_16x16x32_bf16 v[24:27], v[144:147], v[204:207], v[24:27]
	v_mfma_f32_16x16x32_bf16 v[12:15], v[136:139], v[212:215], v[12:15]
	v_mfma_f32_16x16x32_bf16 v[8:11], v[144:147], v[212:215], v[8:11]
	s_barrier
	s_add_i32 m0, s53, 0x14000
	s_add_u32 s98, s30, s90
	s_addc_u32 s99, s31, s91
	global_load_lds_dwordx4 v180, s[98:99]
	s_add_i32 m0, s53, 0x16000
	s_nop 0
	global_load_lds_dwordx4 v176, s[98:99]
	s_waitcnt vmcnt(6)
	s_barrier
	v_mfma_f32_16x16x32_bf16 v[52:55], v[216:219], v[148:151], v[52:55]
	v_mfma_f32_16x16x32_bf16 v[48:51], v[232:235], v[148:151], v[48:51]
	v_mfma_f32_16x16x32_bf16 v[36:39], v[216:219], v[156:159], v[36:39]
	v_mfma_f32_16x16x32_bf16 v[32:35], v[232:235], v[156:159], v[32:35]
	v_mfma_f32_16x16x32_bf16 v[20:23], v[216:219], v[164:167], v[20:23]
	v_mfma_f32_16x16x32_bf16 v[16:19], v[232:235], v[164:167], v[16:19]
	v_mfma_f32_16x16x32_bf16 v[4:7], v[216:219], v[208:211], v[4:7]
	v_mfma_f32_16x16x32_bf16 v[0:3], v[232:235], v[208:211], v[0:3]
	v_mfma_f32_16x16x32_bf16 v[52:55], v[220:223], v[152:155], v[52:55]
	v_mfma_f32_16x16x32_bf16 v[48:51], v[240:243], v[152:155], v[48:51]
	v_mfma_f32_16x16x32_bf16 v[36:39], v[220:223], v[160:163], v[36:39]
	v_mfma_f32_16x16x32_bf16 v[32:35], v[240:243], v[160:163], v[32:35]
	v_mfma_f32_16x16x32_bf16 v[20:23], v[220:223], v[204:207], v[20:23]
	v_mfma_f32_16x16x32_bf16 v[16:19], v[240:243], v[204:207], v[16:19]
	v_mfma_f32_16x16x32_bf16 v[4:7], v[220:223], v[212:215], v[4:7]
	v_mfma_f32_16x16x32_bf16 v[0:3], v[240:243], v[212:215], v[0:3]
	s_barrier
	ds_read_b128 v[132:135], v252 offset:32768
	ds_read_b128 v[136:139], v252 offset:33792
	ds_read_b128 v[140:143], v252 offset:34816
	ds_read_b128 v[144:147], v252 offset:35840
	s_add_u32 s98, s8, s22
	s_addc_u32 s99, s9, s23
	s_mov_b32 m0, s64
	ds_read_b128 v[148:151], v202 offset:32768
	ds_read_b128 v[152:155], v202 offset:33792
	ds_read_b128 v[156:159], v202 offset:34816
	ds_read_b128 v[160:163], v202 offset:35840
	ds_read_b128 v[164:167], v202 offset:36864
	ds_read_b128 v[204:207], v202 offset:37888
	ds_read_b128 v[208:211], v202 offset:38912
	ds_read_b128 v[212:215], v202 offset:39936
	global_load_lds_dwordx4 v178, s[98:99]
	s_mov_b32 m0, s65
	s_nop 0
	global_load_lds_dwordx4 v174, s[98:99]
	s_waitcnt lgkmcnt(8)
	s_barrier
	s_waitcnt lgkmcnt(0)
	v_mfma_f32_16x16x32_bf16 v[124:127], v[132:135], v[148:151], v[124:127]
	v_mfma_f32_16x16x32_bf16 v[120:123], v[140:143], v[148:151], v[120:123]
	v_mfma_f32_16x16x32_bf16 v[108:111], v[132:135], v[156:159], v[108:111]
	v_mfma_f32_16x16x32_bf16 v[104:107], v[140:143], v[156:159], v[104:107]
	v_mfma_f32_16x16x32_bf16 v[92:95], v[132:135], v[164:167], v[92:95]
	v_mfma_f32_16x16x32_bf16 v[88:91], v[140:143], v[164:167], v[88:91]
	v_mfma_f32_16x16x32_bf16 v[76:79], v[132:135], v[208:211], v[76:79]
	v_mfma_f32_16x16x32_bf16 v[72:75], v[140:143], v[208:211], v[72:75]
	v_mfma_f32_16x16x32_bf16 v[124:127], v[136:139], v[152:155], v[124:127]
	v_mfma_f32_16x16x32_bf16 v[120:123], v[144:147], v[152:155], v[120:123]
	v_mfma_f32_16x16x32_bf16 v[108:111], v[136:139], v[160:163], v[108:111]
	v_mfma_f32_16x16x32_bf16 v[104:107], v[144:147], v[160:163], v[104:107]
	v_mfma_f32_16x16x32_bf16 v[92:95], v[136:139], v[204:207], v[92:95]
	v_mfma_f32_16x16x32_bf16 v[88:91], v[144:147], v[204:207], v[88:91]
	v_mfma_f32_16x16x32_bf16 v[76:79], v[136:139], v[212:215], v[76:79]
	v_mfma_f32_16x16x32_bf16 v[72:75], v[144:147], v[212:215], v[72:75]
	s_barrier
	s_add_i32 m0, s53, 0x17f80
	ds_read_b128 v[216:219], v252 offset:49152
	ds_read_b128 v[220:223], v252 offset:50176
	ds_read_b128 v[232:235], v252 offset:51200
	ds_read_b128 v[240:243], v252 offset:52224
	global_load_lds_dwordx4 v180, s[30:31] offset:128
	s_add_i32 m0, s53, 0x19f80
	s_nop 0
	global_load_lds_dwordx4 v176, s[30:31] offset:128
	s_barrier
	s_waitcnt lgkmcnt(0)
	v_mfma_f32_16x16x32_bf16 v[116:119], v[216:219], v[148:151], v[116:119]
	v_mfma_f32_16x16x32_bf16 v[112:115], v[232:235], v[148:151], v[112:115]
	v_mfma_f32_16x16x32_bf16 v[100:103], v[216:219], v[156:159], v[100:103]
	v_mfma_f32_16x16x32_bf16 v[96:99], v[232:235], v[156:159], v[96:99]
	v_mfma_f32_16x16x32_bf16 v[84:87], v[216:219], v[164:167], v[84:87]
	v_mfma_f32_16x16x32_bf16 v[80:83], v[232:235], v[164:167], v[80:83]
	v_mfma_f32_16x16x32_bf16 v[68:71], v[216:219], v[208:211], v[68:71]
	v_mfma_f32_16x16x32_bf16 v[64:67], v[232:235], v[208:211], v[64:67]
	v_mfma_f32_16x16x32_bf16 v[116:119], v[220:223], v[152:155], v[116:119]
	v_mfma_f32_16x16x32_bf16 v[112:115], v[240:243], v[152:155], v[112:115]
	v_mfma_f32_16x16x32_bf16 v[100:103], v[220:223], v[160:163], v[100:103]
	v_mfma_f32_16x16x32_bf16 v[96:99], v[240:243], v[160:163], v[96:99]
	v_mfma_f32_16x16x32_bf16 v[84:87], v[220:223], v[204:207], v[84:87]
	v_mfma_f32_16x16x32_bf16 v[80:83], v[240:243], v[204:207], v[80:83]
	v_mfma_f32_16x16x32_bf16 v[68:71], v[220:223], v[212:215], v[68:71]
	v_mfma_f32_16x16x32_bf16 v[64:67], v[240:243], v[212:215], v[64:67]
	s_add_i32 m0, s66, 0xffffff80
	s_barrier
	ds_read_b128 v[148:151], v202 offset:49152
	ds_read_b128 v[152:155], v202 offset:50176
	ds_read_b128 v[156:159], v202 offset:51200
	ds_read_b128 v[160:163], v202 offset:52224
	ds_read_b128 v[164:167], v202 offset:53248
	ds_read_b128 v[204:207], v202 offset:54272
	ds_read_b128 v[208:211], v202 offset:55296
	ds_read_b128 v[212:215], v202 offset:56320
	global_load_lds_dwordx4 v178, s[8:9] offset:128
	s_add_i32 m0, s67, 0xffffff80
	s_nop 0
	global_load_lds_dwordx4 v174, s[8:9] offset:128
	s_barrier
	s_waitcnt lgkmcnt(0)
	v_mfma_f32_16x16x32_bf16 v[60:63], v[132:135], v[148:151], v[60:63]
	v_mfma_f32_16x16x32_bf16 v[56:59], v[140:143], v[148:151], v[56:59]
	v_mfma_f32_16x16x32_bf16 v[44:47], v[132:135], v[156:159], v[44:47]
	v_mfma_f32_16x16x32_bf16 v[40:43], v[140:143], v[156:159], v[40:43]
	v_mfma_f32_16x16x32_bf16 v[28:31], v[132:135], v[164:167], v[28:31]
	v_mfma_f32_16x16x32_bf16 v[24:27], v[140:143], v[164:167], v[24:27]
	v_mfma_f32_16x16x32_bf16 v[12:15], v[132:135], v[208:211], v[12:15]
	v_mfma_f32_16x16x32_bf16 v[8:11], v[140:143], v[208:211], v[8:11]
	v_mfma_f32_16x16x32_bf16 v[60:63], v[136:139], v[152:155], v[60:63]
	v_mfma_f32_16x16x32_bf16 v[56:59], v[144:147], v[152:155], v[56:59]
	v_mfma_f32_16x16x32_bf16 v[44:47], v[136:139], v[160:163], v[44:47]
	v_mfma_f32_16x16x32_bf16 v[40:43], v[144:147], v[160:163], v[40:43]
	v_mfma_f32_16x16x32_bf16 v[28:31], v[136:139], v[204:207], v[28:31]
	v_mfma_f32_16x16x32_bf16 v[24:27], v[144:147], v[204:207], v[24:27]
	v_mfma_f32_16x16x32_bf16 v[12:15], v[136:139], v[212:215], v[12:15]
	v_mfma_f32_16x16x32_bf16 v[8:11], v[144:147], v[212:215], v[8:11]
	s_barrier
	s_add_i32 m0, s53, 0x1bf80
	s_add_u32 s98, s30, s90
	s_addc_u32 s99, s31, s91
	global_load_lds_dwordx4 v180, s[98:99] offset:128
	s_add_i32 m0, s53, 0x1df80
	s_nop 0
	global_load_lds_dwordx4 v176, s[98:99] offset:128
	s_waitcnt vmcnt(6)
	s_barrier
	v_mfma_f32_16x16x32_bf16 v[52:55], v[216:219], v[148:151], v[52:55]
	v_mfma_f32_16x16x32_bf16 v[48:51], v[232:235], v[148:151], v[48:51]
	v_mfma_f32_16x16x32_bf16 v[36:39], v[216:219], v[156:159], v[36:39]
	v_mfma_f32_16x16x32_bf16 v[32:35], v[232:235], v[156:159], v[32:35]
	v_mfma_f32_16x16x32_bf16 v[20:23], v[216:219], v[164:167], v[20:23]
	v_mfma_f32_16x16x32_bf16 v[16:19], v[232:235], v[164:167], v[16:19]
	v_mfma_f32_16x16x32_bf16 v[4:7], v[216:219], v[208:211], v[4:7]
	v_mfma_f32_16x16x32_bf16 v[0:3], v[232:235], v[208:211], v[0:3]
	v_mfma_f32_16x16x32_bf16 v[52:55], v[220:223], v[152:155], v[52:55]
	v_mfma_f32_16x16x32_bf16 v[48:51], v[240:243], v[152:155], v[48:51]
	v_mfma_f32_16x16x32_bf16 v[36:39], v[220:223], v[160:163], v[36:39]
	v_mfma_f32_16x16x32_bf16 v[32:35], v[240:243], v[160:163], v[32:35]
	v_mfma_f32_16x16x32_bf16 v[20:23], v[220:223], v[204:207], v[20:23]
	v_mfma_f32_16x16x32_bf16 v[16:19], v[240:243], v[204:207], v[16:19]
	v_mfma_f32_16x16x32_bf16 v[4:7], v[220:223], v[212:215], v[4:7]
	v_mfma_f32_16x16x32_bf16 v[0:3], v[240:243], v[212:215], v[0:3]
	s_add_u32 s4, s4, 0x100
	s_addc_u32 s5, s5, 0
	s_cmp_ge_i32 s38, s68
	s_barrier
	s_cbranch_scc1 .Lkx_exit
	s_mov_b32 s46, s38
	s_andn2_b64 vcc, exec, s[96:97]
	s_cbranch_vccnz .LBB0_760
	s_branch .LBB0_754
